# grid barrier: acquire-side buffer_inv sc1 issued at arrival (overlapped with waiting) instead of after the release
# speedup vs baseline: 1.0171x; 1.0118x over previous
.LBB0_1163:
	s_or_b64 exec, exec, s[4:5]
	buffer_inv sc1
	v_cvt_f32_u32_e32 v4, v2
	s_waitcnt vmcnt(1)
	v_readfirstlane_b32 s2, v3
	v_sub_u32_e32 v3, 0, v2
	v_rcp_iflag_f32_e32 v4, v4
	v_add_u32_e32 v5, s2, v1
	v_mul_f32_e32 v4, 0x4f7ffffe, v4
	v_cvt_u32_f32_e32 v4, v4
	v_mul_lo_u32 v1, v3, v4
	v_mul_hi_u32 v1, v4, v1
	v_add_u32_e32 v1, v4, v1
	v_mul_hi_u32 v1, v5, v1
	v_mul_lo_u32 v3, v1, v2
	v_sub_u32_e32 v3, v5, v3
	v_add_u32_e32 v4, 1, v1
	v_cmp_ge_u32_e32 vcc, v3, v2
	s_nop 1
	v_cndmask_b32_e32 v1, v1, v4, vcc
	v_sub_u32_e32 v4, v3, v2
	v_cndmask_b32_e32 v3, v3, v4, vcc
	v_add_u32_e32 v4, 1, v1
	v_cmp_ge_u32_e32 vcc, v3, v2
	v_add_u32_e32 v3, 1, v5
	s_nop 0
	v_cndmask_b32_e32 v1, v1, v4, vcc
	v_mul_lo_u32 v4, v2, v1
	v_add_u32_e32 v2, v4, v2
	v_cmp_ne_u32_e32 vcc, v3, v2
	s_and_saveexec_b64 s[4:5], vcc
	s_xor_b64 s[4:5], exec, s[4:5]
	s_cbranch_execz .LBB0_1177
	v_readlane_b32 s6, v255, 19
	v_readlane_b32 s7, v255, 20
	s_waitcnt lgkmcnt(0)
	s_nop 3
	global_load_dword v0, v173, s[6:7] sc1
	s_waitcnt vmcnt(0)
	v_cmp_eq_u32_e32 vcc, v0, v1
	s_and_saveexec_b64 s[6:7], vcc
	s_cbranch_execz .LBB0_1176
	s_mov_b32 s2, 1
	s_mov_b64 s[8:9], 0
	s_branch .LBB0_1167

.LBB0_1176:
	s_or_b64 exec, exec, s[6:7]
	s_waitcnt vmcnt(0)
	s_waitcnt vmcnt(0)

.LBB0_1195:
	s_or_b64 exec, exec, s[4:5]
	s_mov_b64 s[4:5], exec
	v_mbcnt_lo_u32_b32 v0, s4, 0
	v_mbcnt_hi_u32_b32 v0, s5, v0
	v_cmp_eq_u32_e32 vcc, 0, v0
	s_waitcnt vmcnt(0)
	s_waitcnt vmcnt(0)
